# S5 scan passes: next sub-block's U rows requested during the current one; 16 scan steps per sub-block read B*u from LDS with early-issued reads and counted waits; pass-3 packed states written after th
# speedup vs baseline: 1.0216x; 1.0045x over previous
.LBB0_954:
	s_add_i32 s0, 0, 0x14800
	v_lshl_add_u32 v1, v65, 5, s0
	v_cmp_gt_u32_e64 s[4:5], 32, v64
	v_mov_b32_e32 v0, 0
	v_add_u32_e32 v16, v1, v50
	v_mov_b32_e32 v4, 0
	v_mov_b32_e32 v5, 0
	v_mov_b32_e32 v6, 0
	v_mov_b32_e32 v7, 0
	s_waitcnt lgkmcnt(0)
	s_barrier
	s_and_saveexec_b64 s[0:1], s[4:5]
	ds_read_b128 v[4:7], v16
	s_or_b64 exec, exec, s[0:1]
	v_mov_b32_e32 v1, 0
	v_mov_b32_e32 v2, 0
	v_mov_b32_e32 v3, 0
	s_and_saveexec_b64 s[0:1], s[4:5]
	ds_read_b128 v[0:3], v16 offset:512
	s_or_b64 exec, exec, s[0:1]
	v_mov_b32_e32 v8, 0
	v_mov_b32_e32 v12, 0
	v_mov_b32_e32 v13, 0
	v_mov_b32_e32 v14, 0
	v_mov_b32_e32 v15, 0
	s_and_saveexec_b64 s[0:1], s[4:5]
	ds_read_b128 v[12:15], v16 offset:1024
	s_or_b64 exec, exec, s[0:1]
	v_mov_b32_e32 v9, 0
	v_mov_b32_e32 v10, 0
	v_mov_b32_e32 v11, 0
	s_and_saveexec_b64 s[0:1], s[4:5]
	ds_read_b128 v[8:11], v16 offset:1536
	s_or_b64 exec, exec, s[0:1]
	v_mov_b32_e32 v18, 0
	v_mov_b32_e32 v22, 0
	v_mov_b32_e32 v23, 0
	v_mov_b32_e32 v24, 0
	v_mov_b32_e32 v25, 0
	s_and_saveexec_b64 s[0:1], s[4:5]
	ds_read_b128 v[22:25], v16 offset:2048
	s_or_b64 exec, exec, s[0:1]
	v_mov_b32_e32 v19, 0
	v_mov_b32_e32 v20, 0
	v_mov_b32_e32 v21, 0
	s_and_saveexec_b64 s[0:1], s[4:5]
	ds_read_b128 v[18:21], v16 offset:2560
	s_or_b64 exec, exec, s[0:1]
	v_mov_b32_e32 v26, 0
	v_mov_b32_e32 v30, 0
	v_mov_b32_e32 v31, 0
	v_mov_b32_e32 v32, 0
	v_mov_b32_e32 v33, 0
	s_and_saveexec_b64 s[0:1], s[4:5]
	ds_read_b128 v[30:33], v16 offset:3072
	s_or_b64 exec, exec, s[0:1]
	s_mov_b32 s36, 0
	v_mov_b32_e32 v27, 0
	v_mov_b32_e32 v28, 0
	v_mov_b32_e32 v29, 0
	s_and_saveexec_b64 s[0:1], s[4:5]
	ds_read_b128 v[26:29], v16 offset:3584
	s_or_b64 exec, exec, s[0:1]
	s_ashr_i32 s35, s35, 6
	s_mul_i32 s0, s35, 0x2100
	s_add_i32 s22, s0, 0
	s_add_i32 s0, s22, 0x15800
	v_lshl_add_u32 v34, v65, 2, s0
	s_lshl_b32 s0, s34, 6
	s_lshl_b32 s23, s35, 8
	s_and_b32 s24, s0, 0xfffff800
	s_lshl_b32 s0, s25, 1
	s_add_u32 s0, s28, s0
	v_lshrrev_b32_e32 v60, 4, v64
	s_addc_u32 s1, s29, 0
	v_and_b32_e32 v16, 48, v64
	v_lshl_add_u64 v[58:59], s[0:1], 0, v[16:17]
	v_mul_u32_u24_e32 v16, 0x840, v60
	v_lshlrev_b32_e32 v67, 2, v64
	v_or_b32_e32 v61, s24, v65
	v_mov_b32_e32 v55, v54
	v_mov_b32_e32 v57, v56
	v_add_u32_e32 v87, s22, v67
	v_add_u32_e32 v68, v34, v16
	v_add_u32_e32 v132, s23, v61
	v_ashrrev_i32_e32 v133, 31, v132
	v_lshlrev_b64 v[132:133], 10, v[132:133]
	v_lshl_add_u64 v[130:131], v[58:59], 0, v[132:133]
	v_mov_b32_e32 v134, 0
	v_mov_b32_e32 v135, 0
	v_mov_b32_e32 v136, 0
	v_mov_b32_e32 v137, 0
	v_add_u32_e32 v154, 0x15800, v87
	s_and_saveexec_b64 s[20:21], s[4:5]
	global_load_dwordx4 v[134:137], v[130:131], off
	s_or_b64 exec, exec, s[20:21]
	v_add_co_u32_e32 v130, vcc, 0x4000, v130
	s_nop 1
	v_addc_co_u32_e32 v131, vcc, 0, v131, vcc

.LBB0_972:
	s_waitcnt vmcnt(0)
	v_mov_b32_e32 v34, v134
	v_mov_b32_e32 v35, v135
	v_mov_b32_e32 v36, v136
	v_mov_b32_e32 v37, v137
	s_and_saveexec_b64 s[20:21], s[4:5]
	global_load_dwordx4 v[134:137], v[130:131], off
	s_or_b64 exec, exec, s[20:21]
	v_add_co_u32_e32 v130, vcc, 0x4000, v130
	s_nop 1
	v_addc_co_u32_e32 v131, vcc, 0, v131, vcc
	s_waitcnt lgkmcnt(0)
	v_mfma_f32_16x16x32_bf16 v[90:93], v[34:37], v[4:7], 0
	v_add_u32_e32 v71, 0x400, v68
	v_mfma_f32_16x16x32_bf16 v[94:97], v[34:37], v[0:3], 0
	s_nop 7
	ds_write2_b32 v68, v90, v94 offset1:16
	ds_write2_b32 v68, v91, v95 offset0:132 offset1:148
	ds_write2_b32 v71, v92, v96 offset0:8 offset1:24
	ds_write2_b32 v71, v93, v97 offset0:140 offset1:156
	v_mfma_f32_16x16x32_bf16 v[90:93], v[34:37], v[12:15], 0
	v_mfma_f32_16x16x32_bf16 v[94:97], v[34:37], v[8:11], 0
	s_nop 7
	ds_write2_b32 v68, v90, v94 offset0:32 offset1:48
	ds_write2_b32 v68, v91, v95 offset0:164 offset1:180
	ds_write2_b32 v71, v92, v96 offset0:40 offset1:56
	ds_write2_b32 v71, v93, v97 offset0:172 offset1:188
	v_mfma_f32_16x16x32_bf16 v[90:93], v[34:37], v[22:25], 0
	v_mfma_f32_16x16x32_bf16 v[94:97], v[34:37], v[18:21], 0
	s_nop 7
	ds_write2_b32 v68, v90, v94 offset0:64 offset1:80
	ds_write2_b32 v68, v91, v95 offset0:196 offset1:212
	ds_write2_b32 v71, v92, v96 offset0:72 offset1:88
	ds_write2_b32 v71, v93, v97 offset0:204 offset1:220
	v_mfma_f32_16x16x32_bf16 v[90:93], v[34:37], v[30:33], 0
	v_mfma_f32_16x16x32_bf16 v[34:37], v[34:37], v[26:29], 0
	s_nop 7
	ds_write2_b32 v68, v90, v34 offset0:96 offset1:112
	ds_write2_b32 v68, v91, v35 offset0:228 offset1:244
	ds_write2_b32 v71, v92, v36 offset0:104 offset1:120
	ds_write2_b32 v71, v93, v37 offset0:236 offset1:252
	s_waitcnt lgkmcnt(0)
	ds_read_b32 v98, v154 offset:0
	ds_read_b32 v99, v154 offset:256
	ds_read_b32 v100, v154 offset:528
	ds_read_b32 v101, v154 offset:784
	ds_read_b32 v102, v154 offset:1056
	ds_read_b32 v103, v154 offset:1312
	ds_read_b32 v104, v154 offset:1584
	ds_read_b32 v105, v154 offset:1840
	ds_read_b32 v106, v154 offset:2112
	ds_read_b32 v107, v154 offset:2368
	ds_read_b32 v108, v154 offset:2640
	ds_read_b32 v109, v154 offset:2896
	ds_read_b32 v110, v154 offset:3168
	ds_read_b32 v111, v154 offset:3424
	v_pk_mul_f32 v[36:37], v[56:57], v[38:39]
	s_nop 0
	v_pk_fma_f32 v[90:91], v[54:55], v[38:39], v[36:37] op_sel:[0,0,1] op_sel_hi:[1,1,0] neg_lo:[0,0,1] neg_hi:[0,0,1]
	v_pk_fma_f32 v[36:37], v[54:55], v[38:39], v[36:37] op_sel:[0,0,1] op_sel_hi:[1,1,0]
	s_nop 0
	v_mov_b32_e32 v91, v37
	s_waitcnt lgkmcnt(12)
	v_pk_add_f32 v[38:39], v[90:91], v[98:99]
	ds_read_b32 v112, v154 offset:3696
	ds_read_b32 v113, v154 offset:3952
	v_pk_mul_f32 v[36:37], v[56:57], v[38:39]
	s_nop 0
	v_pk_fma_f32 v[90:91], v[54:55], v[38:39], v[36:37] op_sel:[0,0,1] op_sel_hi:[1,1,0] neg_lo:[0,0,1] neg_hi:[0,0,1]
	v_pk_fma_f32 v[36:37], v[54:55], v[38:39], v[36:37] op_sel:[0,0,1] op_sel_hi:[1,1,0]
	s_nop 0
	v_mov_b32_e32 v91, v37
	s_waitcnt lgkmcnt(12)
	v_pk_add_f32 v[38:39], v[90:91], v[100:101]
	ds_read_b32 v114, v154 offset:4224
	ds_read_b32 v115, v154 offset:4480
	v_pk_mul_f32 v[36:37], v[56:57], v[38:39]
	s_nop 0
	v_pk_fma_f32 v[90:91], v[54:55], v[38:39], v[36:37] op_sel:[0,0,1] op_sel_hi:[1,1,0] neg_lo:[0,0,1] neg_hi:[0,0,1]
	v_pk_fma_f32 v[36:37], v[54:55], v[38:39], v[36:37] op_sel:[0,0,1] op_sel_hi:[1,1,0]
	s_nop 0
	v_mov_b32_e32 v91, v37
	s_waitcnt lgkmcnt(12)
	v_pk_add_f32 v[38:39], v[90:91], v[102:103]
	ds_read_b32 v116, v154 offset:4752
	ds_read_b32 v117, v154 offset:5008
	v_pk_mul_f32 v[36:37], v[56:57], v[38:39]
	s_nop 0
	v_pk_fma_f32 v[90:91], v[54:55], v[38:39], v[36:37] op_sel:[0,0,1] op_sel_hi:[1,1,0] neg_lo:[0,0,1] neg_hi:[0,0,1]
	v_pk_fma_f32 v[36:37], v[54:55], v[38:39], v[36:37] op_sel:[0,0,1] op_sel_hi:[1,1,0]
	s_nop 0
	v_mov_b32_e32 v91, v37
	s_waitcnt lgkmcnt(12)
	v_pk_add_f32 v[38:39], v[90:91], v[104:105]
	ds_read_b32 v118, v154 offset:5280
	ds_read_b32 v119, v154 offset:5536
	v_pk_mul_f32 v[36:37], v[56:57], v[38:39]
	s_nop 0
	v_pk_fma_f32 v[90:91], v[54:55], v[38:39], v[36:37] op_sel:[0,0,1] op_sel_hi:[1,1,0] neg_lo:[0,0,1] neg_hi:[0,0,1]
	v_pk_fma_f32 v[36:37], v[54:55], v[38:39], v[36:37] op_sel:[0,0,1] op_sel_hi:[1,1,0]
	s_nop 0
	v_mov_b32_e32 v91, v37
	s_waitcnt lgkmcnt(12)
	v_pk_add_f32 v[38:39], v[90:91], v[106:107]
	ds_read_b32 v120, v154 offset:5808
	ds_read_b32 v121, v154 offset:6064
	v_pk_mul_f32 v[36:37], v[56:57], v[38:39]
	s_nop 0
	v_pk_fma_f32 v[90:91], v[54:55], v[38:39], v[36:37] op_sel:[0,0,1] op_sel_hi:[1,1,0] neg_lo:[0,0,1] neg_hi:[0,0,1]
	v_pk_fma_f32 v[36:37], v[54:55], v[38:39], v[36:37] op_sel:[0,0,1] op_sel_hi:[1,1,0]
	s_nop 0
	v_mov_b32_e32 v91, v37
	s_waitcnt lgkmcnt(12)
	v_pk_add_f32 v[38:39], v[90:91], v[108:109]
	ds_read_b32 v122, v154 offset:6336
	ds_read_b32 v123, v154 offset:6592
	v_pk_mul_f32 v[36:37], v[56:57], v[38:39]
	s_nop 0
	v_pk_fma_f32 v[90:91], v[54:55], v[38:39], v[36:37] op_sel:[0,0,1] op_sel_hi:[1,1,0] neg_lo:[0,0,1] neg_hi:[0,0,1]
	v_pk_fma_f32 v[36:37], v[54:55], v[38:39], v[36:37] op_sel:[0,0,1] op_sel_hi:[1,1,0]
	s_nop 0
	v_mov_b32_e32 v91, v37
	s_waitcnt lgkmcnt(12)
	v_pk_add_f32 v[38:39], v[90:91], v[110:111]
	ds_read_b32 v124, v154 offset:6864
	ds_read_b32 v125, v154 offset:7120
	v_pk_mul_f32 v[36:37], v[56:57], v[38:39]
	s_nop 0
	v_pk_fma_f32 v[90:91], v[54:55], v[38:39], v[36:37] op_sel:[0,0,1] op_sel_hi:[1,1,0] neg_lo:[0,0,1] neg_hi:[0,0,1]
	v_pk_fma_f32 v[36:37], v[54:55], v[38:39], v[36:37] op_sel:[0,0,1] op_sel_hi:[1,1,0]
	s_nop 0
	v_mov_b32_e32 v91, v37
	s_waitcnt lgkmcnt(12)
	v_pk_add_f32 v[38:39], v[90:91], v[112:113]
	ds_read_b32 v126, v154 offset:7392
	ds_read_b32 v127, v154 offset:7648
	v_pk_mul_f32 v[36:37], v[56:57], v[38:39]
	s_nop 0
	v_pk_fma_f32 v[90:91], v[54:55], v[38:39], v[36:37] op_sel:[0,0,1] op_sel_hi:[1,1,0] neg_lo:[0,0,1] neg_hi:[0,0,1]
	v_pk_fma_f32 v[36:37], v[54:55], v[38:39], v[36:37] op_sel:[0,0,1] op_sel_hi:[1,1,0]
	s_nop 0
	v_mov_b32_e32 v91, v37
	s_waitcnt lgkmcnt(12)
	v_pk_add_f32 v[38:39], v[90:91], v[114:115]
	ds_read_b32 v128, v154 offset:7920
	ds_read_b32 v129, v154 offset:8176
	v_pk_mul_f32 v[36:37], v[56:57], v[38:39]
	s_nop 0
	v_pk_fma_f32 v[90:91], v[54:55], v[38:39], v[36:37] op_sel:[0,0,1] op_sel_hi:[1,1,0] neg_lo:[0,0,1] neg_hi:[0,0,1]
	v_pk_fma_f32 v[36:37], v[54:55], v[38:39], v[36:37] op_sel:[0,0,1] op_sel_hi:[1,1,0]
	s_nop 0
	v_mov_b32_e32 v91, v37
	s_waitcnt lgkmcnt(12)
	v_pk_add_f32 v[38:39], v[90:91], v[116:117]
	v_pk_mul_f32 v[36:37], v[56:57], v[38:39]
	s_nop 0
	v_pk_fma_f32 v[90:91], v[54:55], v[38:39], v[36:37] op_sel:[0,0,1] op_sel_hi:[1,1,0] neg_lo:[0,0,1] neg_hi:[0,0,1]
	v_pk_fma_f32 v[36:37], v[54:55], v[38:39], v[36:37] op_sel:[0,0,1] op_sel_hi:[1,1,0]
	s_nop 0
	v_mov_b32_e32 v91, v37
	s_waitcnt lgkmcnt(10)
	v_pk_add_f32 v[38:39], v[90:91], v[118:119]
	v_pk_mul_f32 v[36:37], v[56:57], v[38:39]
	s_nop 0
	v_pk_fma_f32 v[90:91], v[54:55], v[38:39], v[36:37] op_sel:[0,0,1] op_sel_hi:[1,1,0] neg_lo:[0,0,1] neg_hi:[0,0,1]
	v_pk_fma_f32 v[36:37], v[54:55], v[38:39], v[36:37] op_sel:[0,0,1] op_sel_hi:[1,1,0]
	s_nop 0
	v_mov_b32_e32 v91, v37
	s_waitcnt lgkmcnt(8)
	v_pk_add_f32 v[38:39], v[90:91], v[120:121]
	v_pk_mul_f32 v[36:37], v[56:57], v[38:39]
	s_nop 0
	v_pk_fma_f32 v[90:91], v[54:55], v[38:39], v[36:37] op_sel:[0,0,1] op_sel_hi:[1,1,0] neg_lo:[0,0,1] neg_hi:[0,0,1]
	v_pk_fma_f32 v[36:37], v[54:55], v[38:39], v[36:37] op_sel:[0,0,1] op_sel_hi:[1,1,0]
	s_nop 0
	v_mov_b32_e32 v91, v37
	s_waitcnt lgkmcnt(6)
	v_pk_add_f32 v[38:39], v[90:91], v[122:123]
	v_pk_mul_f32 v[36:37], v[56:57], v[38:39]
	s_nop 0
	v_pk_fma_f32 v[90:91], v[54:55], v[38:39], v[36:37] op_sel:[0,0,1] op_sel_hi:[1,1,0] neg_lo:[0,0,1] neg_hi:[0,0,1]
	v_pk_fma_f32 v[36:37], v[54:55], v[38:39], v[36:37] op_sel:[0,0,1] op_sel_hi:[1,1,0]
	s_nop 0
	v_mov_b32_e32 v91, v37
	s_waitcnt lgkmcnt(4)
	v_pk_add_f32 v[38:39], v[90:91], v[124:125]
	v_pk_mul_f32 v[36:37], v[56:57], v[38:39]
	s_nop 0
	v_pk_fma_f32 v[90:91], v[54:55], v[38:39], v[36:37] op_sel:[0,0,1] op_sel_hi:[1,1,0] neg_lo:[0,0,1] neg_hi:[0,0,1]
	v_pk_fma_f32 v[36:37], v[54:55], v[38:39], v[36:37] op_sel:[0,0,1] op_sel_hi:[1,1,0]
	s_nop 0
	v_mov_b32_e32 v91, v37
	s_waitcnt lgkmcnt(2)
	v_pk_add_f32 v[38:39], v[90:91], v[126:127]
	v_pk_mul_f32 v[36:37], v[56:57], v[38:39]
	s_nop 0
	v_pk_fma_f32 v[90:91], v[54:55], v[38:39], v[36:37] op_sel:[0,0,1] op_sel_hi:[1,1,0] neg_lo:[0,0,1] neg_hi:[0,0,1]
	v_pk_fma_f32 v[36:37], v[54:55], v[38:39], v[36:37] op_sel:[0,0,1] op_sel_hi:[1,1,0]
	s_nop 0
	v_mov_b32_e32 v91, v37
	s_waitcnt lgkmcnt(0)
	v_pk_add_f32 v[38:39], v[90:91], v[128:129]
	s_add_i32 s38, s38, 1
	s_cmp_eq_u32 s38, 4
	s_cbranch_scc0 .LBB0_972
	v_or_b32_e32 v16, s37, v64
	s_add_i32 s36, s36, 1
	v_lshl_add_u32 v16, v16, 3, 0
	s_cmp_eq_u32 s36, 4
	ds_write_b64 v16, v[38:39]
	s_cbranch_scc0 .LBB0_971
	s_andn2_b64 vcc, exec, s[2:3]
	s_waitcnt lgkmcnt(0)
	s_barrier
	s_cbranch_vccnz .LBB0_980
	v_mov_b32_e32 v34, v56
	v_mov_b32_e32 v35, v55
	v_pk_mul_f32 v[36:37], v[34:35], v[34:35] op_sel:[1,0] op_sel_hi:[0,0]
	v_pk_fma_f32 v[38:39], v[54:55], v[34:35], v[36:37]
	v_pk_fma_f32 v[34:35], v[54:55], v[34:35], v[36:37] neg_lo:[0,0,1] neg_hi:[0,0,1]
	v_mov_b32_e32 v36, v38
	v_pk_mov_b32 v[88:89], v[34:35], v[38:39] op_sel:[1,0]
	v_mov_b32_e32 v37, v35
	v_pk_mul_f32 v[38:39], v[38:39], v[88:89] op_sel_hi:[0,1]
	v_pk_fma_f32 v[88:89], v[36:37], v[34:35], v[38:39] op_sel:[0,1,0]
	v_pk_fma_f32 v[34:35], v[36:37], v[34:35], v[38:39] op_sel:[0,1,0] neg_lo:[0,0,1] neg_hi:[0,0,1]
	v_mov_b32_e32 v36, v88
	v_pk_mov_b32 v[38:39], v[34:35], v[88:89] op_sel:[1,0]
	v_mov_b32_e32 v37, v35
	v_pk_mul_f32 v[38:39], v[88:89], v[38:39] op_sel_hi:[0,1]
	v_pk_fma_f32 v[88:89], v[36:37], v[34:35], v[38:39] op_sel:[0,1,0]
	v_pk_fma_f32 v[34:35], v[36:37], v[34:35], v[38:39] op_sel:[0,1,0] neg_lo:[0,0,1] neg_hi:[0,0,1]
	v_mov_b32_e32 v36, v88
	v_pk_mov_b32 v[38:39], v[34:35], v[88:89] op_sel:[1,0]
	v_mov_b32_e32 v37, v35
	v_pk_mul_f32 v[38:39], v[88:89], v[38:39] op_sel_hi:[0,1]
	v_pk_fma_f32 v[88:89], v[36:37], v[34:35], v[38:39] op_sel:[0,1,0]
	v_pk_fma_f32 v[34:35], v[36:37], v[34:35], v[38:39] op_sel:[0,1,0] neg_lo:[0,0,1] neg_hi:[0,0,1]
	v_mov_b32_e32 v36, v88
	v_pk_mov_b32 v[38:39], v[34:35], v[88:89] op_sel:[1,0]
	v_mov_b32_e32 v37, v35
	v_pk_mul_f32 v[38:39], v[88:89], v[38:39] op_sel_hi:[0,1]
	v_pk_fma_f32 v[88:89], v[88:89], v[34:35], v[38:39] op_sel:[0,1,0]
	v_pk_fma_f32 v[36:37], v[36:37], v[34:35], v[38:39] op_sel:[0,1,0] neg_lo:[0,0,1] neg_hi:[0,0,1]
	v_lshl_add_u32 v38, v64, 3, 0
	v_mov_b32_e32 v89, v37
	v_mul_f32_e32 v16, v37, v37
	v_pk_fma_f32 v[34:35], v[88:89], v[88:89], v[16:17] op_sel_hi:[1,1,0] neg_lo:[1,0,0] neg_hi:[1,0,0]
	v_pk_mul_f32 v[36:37], v[88:89], v[36:37] op_sel:[0,1] op_sel_hi:[1,0]
	ds_read2st64_b64 v[88:91], v38 offset1:1
	v_pk_add_f32 v[36:37], v[36:37], v[36:37]
	v_mul_f32_e32 v39, 0, v34
	v_mul_f32_e32 v93, 0, v36
	v_sub_f32_e32 v92, v39, v93
	v_fmac_f32_e32 v93, 0, v34
	s_waitcnt lgkmcnt(0)
	v_pk_add_f32 v[88:89], v[92:93], v[88:89]
	v_mov_b32_e32 v16, v17
	v_pk_mul_f32 v[92:93], v[36:37], v[88:89] op_sel_hi:[0,1]
	ds_write2st64_b64 v38, v[16:17], v[88:89] offset1:1
	v_pk_fma_f32 v[94:95], v[34:35], v[88:89], v[92:93] op_sel:[0,0,1] op_sel_hi:[1,1,0] neg_lo:[0,0,1] neg_hi:[0,0,1]
	v_pk_fma_f32 v[88:89], v[34:35], v[88:89], v[92:93] op_sel:[0,0,1] op_sel_hi:[0,1,0]
	v_mov_b32_e32 v95, v89
	v_pk_add_f32 v[92:93], v[94:95], v[90:91]
	ds_read2st64_b64 v[88:91], v38 offset0:2 offset1:3
	v_pk_mul_f32 v[94:95], v[36:37], v[92:93] op_sel_hi:[0,1]
	v_pk_fma_f32 v[96:97], v[34:35], v[92:93], v[94:95] op_sel:[0,0,1] op_sel_hi:[1,1,0] neg_lo:[0,0,1] neg_hi:[0,0,1]
	v_pk_fma_f32 v[94:95], v[34:35], v[92:93], v[94:95] op_sel:[0,0,1] op_sel_hi:[0,1,0]
	v_mov_b32_e32 v97, v95
	s_waitcnt lgkmcnt(0)
	v_pk_add_f32 v[88:89], v[96:97], v[88:89]
	ds_write2st64_b64 v38, v[92:93], v[88:89] offset0:2 offset1:3
	v_pk_mul_f32 v[92:93], v[36:37], v[88:89] op_sel_hi:[0,1]
	v_pk_fma_f32 v[94:95], v[34:35], v[88:89], v[92:93] op_sel:[0,0,1] op_sel_hi:[1,1,0] neg_lo:[0,0,1] neg_hi:[0,0,1]
	v_pk_fma_f32 v[88:89], v[34:35], v[88:89], v[92:93] op_sel:[0,0,1] op_sel_hi:[0,1,0]
	v_mov_b32_e32 v95, v89
	v_pk_add_f32 v[92:93], v[94:95], v[90:91]
	ds_read2st64_b64 v[88:91], v38 offset0:4 offset1:5
	v_pk_mul_f32 v[94:95], v[36:37], v[92:93] op_sel_hi:[0,1]
	v_pk_fma_f32 v[96:97], v[34:35], v[92:93], v[94:95] op_sel:[0,0,1] op_sel_hi:[1,1,0] neg_lo:[0,0,1] neg_hi:[0,0,1]
	v_pk_fma_f32 v[94:95], v[34:35], v[92:93], v[94:95] op_sel:[0,0,1] op_sel_hi:[0,1,0]
	v_mov_b32_e32 v97, v95
	s_waitcnt lgkmcnt(0)
	v_pk_add_f32 v[88:89], v[96:97], v[88:89]
	ds_write2st64_b64 v38, v[92:93], v[88:89] offset0:4 offset1:5
	v_pk_mul_f32 v[92:93], v[36:37], v[88:89] op_sel_hi:[0,1]
	v_pk_fma_f32 v[94:95], v[34:35], v[88:89], v[92:93] op_sel:[0,0,1] op_sel_hi:[1,1,0] neg_lo:[0,0,1] neg_hi:[0,0,1]
	v_pk_fma_f32 v[88:89], v[34:35], v[88:89], v[92:93] op_sel:[0,0,1] op_sel_hi:[0,1,0]
	v_mov_b32_e32 v95, v89
	v_pk_add_f32 v[92:93], v[94:95], v[90:91]
	ds_read2st64_b64 v[88:91], v38 offset0:6 offset1:7
	v_pk_mul_f32 v[94:95], v[36:37], v[92:93] op_sel_hi:[0,1]
	v_pk_fma_f32 v[96:97], v[34:35], v[92:93], v[94:95] op_sel:[0,0,1] op_sel_hi:[1,1,0] neg_lo:[0,0,1] neg_hi:[0,0,1]
	v_pk_fma_f32 v[94:95], v[34:35], v[92:93], v[94:95] op_sel:[0,0,1] op_sel_hi:[0,1,0]
	v_mov_b32_e32 v97, v95
	s_waitcnt lgkmcnt(0)
	v_pk_add_f32 v[88:89], v[96:97], v[88:89]
	ds_write2st64_b64 v38, v[92:93], v[88:89] offset0:6 offset1:7
	v_pk_mul_f32 v[92:93], v[36:37], v[88:89] op_sel_hi:[0,1]
	v_pk_fma_f32 v[94:95], v[34:35], v[88:89], v[92:93] op_sel:[0,0,1] op_sel_hi:[1,1,0] neg_lo:[0,0,1] neg_hi:[0,0,1]
	v_pk_fma_f32 v[88:89], v[34:35], v[88:89], v[92:93] op_sel:[0,0,1] op_sel_hi:[0,1,0]
	v_mov_b32_e32 v95, v89
	v_pk_add_f32 v[92:93], v[94:95], v[90:91]
	ds_read2st64_b64 v[88:91], v38 offset0:8 offset1:9
	v_pk_mul_f32 v[94:95], v[36:37], v[92:93] op_sel_hi:[0,1]
	v_pk_fma_f32 v[96:97], v[34:35], v[92:93], v[94:95] op_sel:[0,0,1] op_sel_hi:[1,1,0] neg_lo:[0,0,1] neg_hi:[0,0,1]
	v_pk_fma_f32 v[94:95], v[34:35], v[92:93], v[94:95] op_sel:[0,0,1] op_sel_hi:[0,1,0]
	v_mov_b32_e32 v97, v95
	s_waitcnt lgkmcnt(0)
	v_pk_add_f32 v[88:89], v[96:97], v[88:89]
	ds_write2st64_b64 v38, v[92:93], v[88:89] offset0:8 offset1:9
	v_pk_mul_f32 v[92:93], v[36:37], v[88:89] op_sel_hi:[0,1]
	v_pk_fma_f32 v[94:95], v[34:35], v[88:89], v[92:93] op_sel:[0,0,1] op_sel_hi:[1,1,0] neg_lo:[0,0,1] neg_hi:[0,0,1]
	v_pk_fma_f32 v[88:89], v[34:35], v[88:89], v[92:93] op_sel:[0,0,1] op_sel_hi:[0,1,0]
	v_mov_b32_e32 v95, v89
	v_pk_add_f32 v[92:93], v[94:95], v[90:91]
	ds_read2st64_b64 v[88:91], v38 offset0:10 offset1:11
	v_pk_mul_f32 v[94:95], v[36:37], v[92:93] op_sel_hi:[0,1]
	v_pk_fma_f32 v[96:97], v[34:35], v[92:93], v[94:95] op_sel:[0,0,1] op_sel_hi:[1,1,0] neg_lo:[0,0,1] neg_hi:[0,0,1]
	v_pk_fma_f32 v[94:95], v[34:35], v[92:93], v[94:95] op_sel:[0,0,1] op_sel_hi:[0,1,0]
	v_mov_b32_e32 v97, v95
	s_waitcnt lgkmcnt(0)
	v_pk_add_f32 v[88:89], v[96:97], v[88:89]
	ds_write2st64_b64 v38, v[92:93], v[88:89] offset0:10 offset1:11
	v_pk_mul_f32 v[92:93], v[36:37], v[88:89] op_sel_hi:[0,1]
	v_pk_fma_f32 v[94:95], v[34:35], v[88:89], v[92:93] op_sel:[0,0,1] op_sel_hi:[1,1,0] neg_lo:[0,0,1] neg_hi:[0,0,1]
	v_pk_fma_f32 v[88:89], v[34:35], v[88:89], v[92:93] op_sel:[0,0,1] op_sel_hi:[0,1,0]
	v_mov_b32_e32 v95, v89
	v_pk_add_f32 v[92:93], v[94:95], v[90:91]
	ds_read2st64_b64 v[88:91], v38 offset0:12 offset1:13
	v_pk_mul_f32 v[94:95], v[36:37], v[92:93] op_sel_hi:[0,1]
	v_pk_fma_f32 v[96:97], v[34:35], v[92:93], v[94:95] op_sel:[0,0,1] op_sel_hi:[1,1,0] neg_lo:[0,0,1] neg_hi:[0,0,1]
	v_pk_fma_f32 v[94:95], v[34:35], v[92:93], v[94:95] op_sel:[0,0,1] op_sel_hi:[0,1,0]
	v_mov_b32_e32 v97, v95
	s_waitcnt lgkmcnt(0)
	v_pk_add_f32 v[88:89], v[96:97], v[88:89]
	ds_write2st64_b64 v38, v[92:93], v[88:89] offset0:12 offset1:13
	v_pk_mul_f32 v[92:93], v[36:37], v[88:89] op_sel_hi:[0,1]
	v_pk_fma_f32 v[94:95], v[34:35], v[88:89], v[92:93] op_sel:[0,0,1] op_sel_hi:[1,1,0] neg_lo:[0,0,1] neg_hi:[0,0,1]
	v_pk_fma_f32 v[88:89], v[34:35], v[88:89], v[92:93] op_sel:[0,0,1] op_sel_hi:[0,1,0]
	v_mov_b32_e32 v95, v89
	v_pk_add_f32 v[92:93], v[94:95], v[90:91]
	ds_read2st64_b64 v[88:91], v38 offset0:14 offset1:15
	v_pk_mul_f32 v[94:95], v[36:37], v[92:93] op_sel_hi:[0,1]
	v_pk_fma_f32 v[96:97], v[34:35], v[92:93], v[94:95] op_sel:[0,0,1] op_sel_hi:[1,1,0] neg_lo:[0,0,1] neg_hi:[0,0,1]
	v_pk_fma_f32 v[94:95], v[34:35], v[92:93], v[94:95] op_sel:[0,0,1] op_sel_hi:[0,1,0]
	v_mov_b32_e32 v97, v95
	s_waitcnt lgkmcnt(0)
	v_pk_add_f32 v[88:89], v[96:97], v[88:89]
	ds_write2st64_b64 v38, v[92:93], v[88:89] offset0:14 offset1:15
	v_pk_mul_f32 v[92:93], v[36:37], v[88:89] op_sel_hi:[0,1]
	v_pk_fma_f32 v[94:95], v[34:35], v[88:89], v[92:93] op_sel:[0,0,1] op_sel_hi:[1,1,0] neg_lo:[0,0,1] neg_hi:[0,0,1]
	v_pk_fma_f32 v[88:89], v[34:35], v[88:89], v[92:93] op_sel:[0,0,1] op_sel_hi:[0,1,0]
	v_mov_b32_e32 v95, v89
	v_pk_add_f32 v[92:93], v[94:95], v[90:91]
	ds_read2st64_b64 v[88:91], v38 offset0:16 offset1:17
	v_pk_mul_f32 v[94:95], v[36:37], v[92:93] op_sel_hi:[0,1]
	v_pk_fma_f32 v[96:97], v[34:35], v[92:93], v[94:95] op_sel:[0,0,1] op_sel_hi:[1,1,0] neg_lo:[0,0,1] neg_hi:[0,0,1]
	v_pk_fma_f32 v[94:95], v[34:35], v[92:93], v[94:95] op_sel:[0,0,1] op_sel_hi:[0,1,0]
	v_mov_b32_e32 v97, v95
	s_waitcnt lgkmcnt(0)
	v_pk_add_f32 v[88:89], v[96:97], v[88:89]
	ds_write2st64_b64 v38, v[92:93], v[88:89] offset0:16 offset1:17
	v_pk_mul_f32 v[92:93], v[36:37], v[88:89] op_sel_hi:[0,1]
	v_pk_fma_f32 v[94:95], v[34:35], v[88:89], v[92:93] op_sel:[0,0,1] op_sel_hi:[1,1,0] neg_lo:[0,0,1] neg_hi:[0,0,1]
	v_pk_fma_f32 v[88:89], v[34:35], v[88:89], v[92:93] op_sel:[0,0,1] op_sel_hi:[0,1,0]
	v_mov_b32_e32 v95, v89
	v_pk_add_f32 v[92:93], v[94:95], v[90:91]
	ds_read2st64_b64 v[88:91], v38 offset0:18 offset1:19
	v_pk_mul_f32 v[94:95], v[36:37], v[92:93] op_sel_hi:[0,1]
	v_pk_fma_f32 v[96:97], v[34:35], v[92:93], v[94:95] op_sel:[0,0,1] op_sel_hi:[1,1,0] neg_lo:[0,0,1] neg_hi:[0,0,1]
	v_pk_fma_f32 v[94:95], v[34:35], v[92:93], v[94:95] op_sel:[0,0,1] op_sel_hi:[0,1,0]
	v_mov_b32_e32 v97, v95
	s_waitcnt lgkmcnt(0)
	v_pk_add_f32 v[88:89], v[96:97], v[88:89]
	ds_write2st64_b64 v38, v[92:93], v[88:89] offset0:18 offset1:19
	v_pk_mul_f32 v[92:93], v[36:37], v[88:89] op_sel_hi:[0,1]
	v_pk_fma_f32 v[94:95], v[34:35], v[88:89], v[92:93] op_sel:[0,0,1] op_sel_hi:[1,1,0] neg_lo:[0,0,1] neg_hi:[0,0,1]
	v_pk_fma_f32 v[88:89], v[34:35], v[88:89], v[92:93] op_sel:[0,0,1] op_sel_hi:[0,1,0]
	v_mov_b32_e32 v95, v89
	v_pk_add_f32 v[92:93], v[94:95], v[90:91]
	ds_read2st64_b64 v[88:91], v38 offset0:20 offset1:21
	v_pk_mul_f32 v[94:95], v[36:37], v[92:93] op_sel_hi:[0,1]
	v_pk_fma_f32 v[96:97], v[34:35], v[92:93], v[94:95] op_sel:[0,0,1] op_sel_hi:[1,1,0] neg_lo:[0,0,1] neg_hi:[0,0,1]
	v_pk_fma_f32 v[94:95], v[34:35], v[92:93], v[94:95] op_sel:[0,0,1] op_sel_hi:[0,1,0]
	v_mov_b32_e32 v97, v95
	s_waitcnt lgkmcnt(0)
	v_pk_add_f32 v[88:89], v[96:97], v[88:89]
	ds_write2st64_b64 v38, v[92:93], v[88:89] offset0:20 offset1:21
	v_pk_mul_f32 v[92:93], v[36:37], v[88:89] op_sel_hi:[0,1]
	v_pk_fma_f32 v[94:95], v[34:35], v[88:89], v[92:93] op_sel:[0,0,1] op_sel_hi:[1,1,0] neg_lo:[0,0,1] neg_hi:[0,0,1]
	v_pk_fma_f32 v[88:89], v[34:35], v[88:89], v[92:93] op_sel:[0,0,1] op_sel_hi:[0,1,0]
	v_mov_b32_e32 v95, v89
	v_pk_add_f32 v[92:93], v[94:95], v[90:91]
	ds_read2st64_b64 v[88:91], v38 offset0:22 offset1:23
	v_pk_mul_f32 v[94:95], v[36:37], v[92:93] op_sel_hi:[0,1]
	v_pk_fma_f32 v[96:97], v[34:35], v[92:93], v[94:95] op_sel:[0,0,1] op_sel_hi:[1,1,0] neg_lo:[0,0,1] neg_hi:[0,0,1]
	v_pk_fma_f32 v[94:95], v[34:35], v[92:93], v[94:95] op_sel:[0,0,1] op_sel_hi:[0,1,0]
	v_mov_b32_e32 v97, v95
	s_waitcnt lgkmcnt(0)
	v_pk_add_f32 v[88:89], v[96:97], v[88:89]
	ds_write2st64_b64 v38, v[92:93], v[88:89] offset0:22 offset1:23
	v_pk_mul_f32 v[92:93], v[36:37], v[88:89] op_sel_hi:[0,1]
	v_pk_fma_f32 v[94:95], v[34:35], v[88:89], v[92:93] op_sel:[0,0,1] op_sel_hi:[1,1,0] neg_lo:[0,0,1] neg_hi:[0,0,1]
	v_pk_fma_f32 v[88:89], v[34:35], v[88:89], v[92:93] op_sel:[0,0,1] op_sel_hi:[0,1,0]
	v_mov_b32_e32 v95, v89
	v_pk_add_f32 v[92:93], v[94:95], v[90:91]
	ds_read2st64_b64 v[88:91], v38 offset0:24 offset1:25
	v_pk_mul_f32 v[94:95], v[36:37], v[92:93] op_sel_hi:[0,1]
	v_pk_fma_f32 v[96:97], v[34:35], v[92:93], v[94:95] op_sel:[0,0,1] op_sel_hi:[1,1,0] neg_lo:[0,0,1] neg_hi:[0,0,1]
	v_pk_fma_f32 v[94:95], v[34:35], v[92:93], v[94:95] op_sel:[0,0,1] op_sel_hi:[0,1,0]
	v_mov_b32_e32 v97, v95
	s_waitcnt lgkmcnt(0)
	v_pk_add_f32 v[88:89], v[96:97], v[88:89]
	ds_write2st64_b64 v38, v[92:93], v[88:89] offset0:24 offset1:25
	v_pk_mul_f32 v[92:93], v[36:37], v[88:89] op_sel_hi:[0,1]
	v_pk_fma_f32 v[94:95], v[34:35], v[88:89], v[92:93] op_sel:[0,0,1] op_sel_hi:[1,1,0] neg_lo:[0,0,1] neg_hi:[0,0,1]
	v_pk_fma_f32 v[88:89], v[34:35], v[88:89], v[92:93] op_sel:[0,0,1] op_sel_hi:[0,1,0]
	v_mov_b32_e32 v95, v89
	v_pk_add_f32 v[92:93], v[94:95], v[90:91]
	ds_read2st64_b64 v[88:91], v38 offset0:26 offset1:27
	v_pk_mul_f32 v[94:95], v[36:37], v[92:93] op_sel_hi:[0,1]
	v_pk_fma_f32 v[96:97], v[34:35], v[92:93], v[94:95] op_sel:[0,0,1] op_sel_hi:[1,1,0] neg_lo:[0,0,1] neg_hi:[0,0,1]
	v_pk_fma_f32 v[94:95], v[34:35], v[92:93], v[94:95] op_sel:[0,0,1] op_sel_hi:[0,1,0]
	v_mov_b32_e32 v97, v95
	s_waitcnt lgkmcnt(0)
	v_pk_add_f32 v[88:89], v[96:97], v[88:89]
	ds_write2st64_b64 v38, v[92:93], v[88:89] offset0:26 offset1:27
	v_pk_mul_f32 v[92:93], v[36:37], v[88:89] op_sel_hi:[0,1]
	v_pk_fma_f32 v[94:95], v[34:35], v[88:89], v[92:93] op_sel:[0,0,1] op_sel_hi:[1,1,0] neg_lo:[0,0,1] neg_hi:[0,0,1]
	v_pk_fma_f32 v[88:89], v[34:35], v[88:89], v[92:93] op_sel:[0,0,1] op_sel_hi:[0,1,0]
	v_mov_b32_e32 v95, v89
	v_pk_add_f32 v[92:93], v[94:95], v[90:91]
	ds_read2st64_b64 v[88:91], v38 offset0:28 offset1:29
	v_pk_mul_f32 v[94:95], v[36:37], v[92:93] op_sel_hi:[0,1]
	v_pk_fma_f32 v[96:97], v[34:35], v[92:93], v[94:95] op_sel:[0,0,1] op_sel_hi:[1,1,0] neg_lo:[0,0,1] neg_hi:[0,0,1]
	v_pk_fma_f32 v[94:95], v[34:35], v[92:93], v[94:95] op_sel:[0,0,1] op_sel_hi:[0,1,0]
	v_mov_b32_e32 v97, v95
	s_waitcnt lgkmcnt(0)
	v_pk_add_f32 v[88:89], v[96:97], v[88:89]
	ds_write2st64_b64 v38, v[92:93], v[88:89] offset0:28 offset1:29
	v_pk_mul_f32 v[92:93], v[36:37], v[88:89] op_sel_hi:[0,1]
	v_pk_fma_f32 v[94:95], v[34:35], v[88:89], v[92:93] op_sel:[0,0,1] op_sel_hi:[1,1,0] neg_lo:[0,0,1] neg_hi:[0,0,1]
	v_pk_fma_f32 v[88:89], v[34:35], v[88:89], v[92:93] op_sel:[0,0,1] op_sel_hi:[0,1,0]
	v_mov_b32_e32 v95, v89
	v_pk_add_f32 v[88:89], v[94:95], v[90:91]
	ds_read_b64 v[90:91], v38 offset:15360
	v_pk_mul_f32 v[36:37], v[36:37], v[88:89] op_sel_hi:[0,1]
	v_pk_fma_f32 v[92:93], v[34:35], v[88:89], v[36:37] op_sel:[0,0,1] op_sel_hi:[1,1,0] neg_lo:[0,0,1] neg_hi:[0,0,1]
	v_pk_fma_f32 v[34:35], v[34:35], v[88:89], v[36:37] op_sel:[0,0,1] op_sel_hi:[0,1,0]
	v_mov_b32_e32 v93, v35
	s_waitcnt lgkmcnt(0)
	v_pk_add_f32 v[34:35], v[92:93], v[90:91]
	ds_write2st64_b64 v38, v[88:89], v[34:35] offset0:30 offset1:31
.LBB0_980:
	s_lshl_b32 s2, s35, 12
	s_add_i32 s36, s2, 0
	s_add_i32 s20, s36, s23
	s_lshl_b32 s2, s25, 1
	s_add_u32 s2, s30, s2
	v_mov_b32_e32 v16, s20
	s_movk_i32 s20, 0x110
	s_addc_u32 s3, s31, 0
	v_mad_u32_u24 v90, v65, s20, v16
	v_lshlrev_b32_e32 v16, 1, v65
	s_mulk_i32 s35, 0x1100
	v_lshlrev_b32_e32 v87, 2, v60
	v_lshlrev_b32_e32 v89, 6, v64
	v_lshl_add_u64 v[60:61], s[2:3], 0, v[16:17]
	s_mov_b32 s2, 0x5040100
	s_add_i32 s20, s35, 0
	v_lshl_add_u32 v88, v65, 2, s36
	v_perm_b32 v37, v47, v46, s2
	v_perm_b32 v36, v45, v44, s2
	v_perm_b32 v35, v43, v42, s2
	v_perm_b32 v34, v41, v40, s2
	v_perm_b32 v41, v69, v63, s2
	v_perm_b32 v40, v62, v53, s2
	v_perm_b32 v39, v52, v51, s2
	v_perm_b32 v38, v49, v48, s2
	v_perm_b32 v45, v82, v80, s2
	v_perm_b32 v44, v78, v77, s2
	v_perm_b32 v43, v75, v73, s2
	v_perm_b32 v42, v72, v70, s2
	v_perm_b32 v49, v86, v85, s2
	v_perm_b32 v48, v84, v83, s2
	v_perm_b32 v47, v81, v79, s2
	v_perm_b32 v46, v76, v74, s2
	s_add_i32 s20, s20, 0xc000
	s_mov_b32 s21, 0
	v_add_u32_e32 v16, s36, v89
	v_add_u32_e32 v69, v90, v50
	s_waitcnt lgkmcnt(0)
	s_barrier
	v_mov_b32_e32 v132, s24
	v_add3_u32 v132, v132, s23, v65
	v_ashrrev_i32_e32 v133, 31, v132
	v_lshlrev_b64 v[132:133], 10, v[132:133]
	v_lshl_add_u64 v[130:131], v[58:59], 0, v[132:133]
	v_mov_b32_e32 v134, 0
	v_mov_b32_e32 v135, 0
	v_mov_b32_e32 v136, 0
	v_mov_b32_e32 v137, 0
	v_add_u32_e32 v154, s22, v67
	v_add_u32_e32 v154, 0x15800, v154
	v_add_u32_e32 v155, s20, v67
	s_and_saveexec_b64 s[2:3], s[4:5]
	global_load_dwordx4 v[134:137], v[130:131], off
	s_or_b64 exec, exec, s[2:3]
	v_add_co_u32_e32 v130, vcc, 0x4000, v130
	s_nop 1
	v_addc_co_u32_e32 v131, vcc, 0, v131, vcc

.LBB0_982:
	s_waitcnt vmcnt(4)
	v_mov_b32_e32 v50, v134
	v_mov_b32_e32 v51, v135
	v_mov_b32_e32 v52, v136
	v_mov_b32_e32 v53, v137
	s_and_saveexec_b64 s[2:3], s[4:5]
	global_load_dwordx4 v[134:137], v[130:131], off
	s_or_b64 exec, exec, s[2:3]
	v_add_co_u32_e32 v130, vcc, 0x4000, v130
	s_nop 1
	v_addc_co_u32_e32 v131, vcc, 0, v131, vcc
	v_mfma_f32_16x16x32_bf16 v[72:75], v[50:53], v[4:7], 0
	v_mfma_f32_16x16x32_bf16 v[76:79], v[50:53], v[0:3], 0
	s_nop 7
	ds_write2_b32 v68, v72, v76 offset1:16
	ds_write2_b32 v68, v73, v77 offset0:132 offset1:148
	ds_write2_b32 v71, v74, v78 offset0:8 offset1:24
	ds_write2_b32 v71, v75, v79 offset0:140 offset1:156
	v_mfma_f32_16x16x32_bf16 v[72:75], v[50:53], v[12:15], 0
	v_mfma_f32_16x16x32_bf16 v[76:79], v[50:53], v[8:11], 0
	s_nop 7
	ds_write2_b32 v68, v72, v76 offset0:32 offset1:48
	ds_write2_b32 v68, v73, v77 offset0:164 offset1:180
	ds_write2_b32 v71, v74, v78 offset0:40 offset1:56
	ds_write2_b32 v71, v75, v79 offset0:172 offset1:188
	v_mfma_f32_16x16x32_bf16 v[72:75], v[50:53], v[22:25], 0
	v_mfma_f32_16x16x32_bf16 v[76:79], v[50:53], v[18:21], 0
	s_nop 7
	ds_write2_b32 v68, v72, v76 offset0:64 offset1:80
	ds_write2_b32 v68, v73, v77 offset0:196 offset1:212
	ds_write2_b32 v71, v74, v78 offset0:72 offset1:88
	ds_write2_b32 v71, v75, v79 offset0:204 offset1:220
	v_mfma_f32_16x16x32_bf16 v[72:75], v[50:53], v[30:33], 0
	v_mfma_f32_16x16x32_bf16 v[50:53], v[50:53], v[26:29], 0
	s_nop 7
	ds_write2_b32 v68, v72, v50 offset0:96 offset1:112
	ds_write2_b32 v68, v73, v51 offset0:228 offset1:244
	ds_write2_b32 v71, v74, v52 offset0:104 offset1:120
	ds_write2_b32 v71, v75, v53 offset0:236 offset1:252
	s_waitcnt lgkmcnt(0)
	ds_read_b32 v98, v154 offset:0
	ds_read_b32 v99, v154 offset:256
	ds_read_b32 v100, v154 offset:528
	ds_read_b32 v101, v154 offset:784
	ds_read_b32 v102, v154 offset:1056
	ds_read_b32 v103, v154 offset:1312
	ds_read_b32 v104, v154 offset:1584
	ds_read_b32 v105, v154 offset:1840
	ds_read_b32 v106, v154 offset:2112
	ds_read_b32 v107, v154 offset:2368
	ds_read_b32 v108, v154 offset:2640
	ds_read_b32 v109, v154 offset:2896
	ds_read_b32 v110, v154 offset:3168
	ds_read_b32 v111, v154 offset:3424
	v_pk_mul_f32 v[52:53], v[56:57], v[62:63]
	s_nop 0
	v_pk_fma_f32 v[72:73], v[54:55], v[62:63], v[52:53] op_sel:[0,0,1] op_sel_hi:[1,1,0] neg_lo:[0,0,1] neg_hi:[0,0,1]
	v_pk_fma_f32 v[52:53], v[54:55], v[62:63], v[52:53] op_sel:[0,0,1] op_sel_hi:[1,1,0]
	s_nop 0
	v_mov_b32_e32 v73, v53
	s_waitcnt lgkmcnt(12)
	v_pk_add_f32 v[62:63], v[72:73], v[98:99]
	ds_read_b32 v112, v154 offset:3696
	ds_read_b32 v113, v154 offset:3952
	s_nop 0
	v_cvt_pk_bf16_f32 v138, v62, v63
	v_pk_mul_f32 v[52:53], v[56:57], v[62:63]
	s_nop 0
	v_pk_fma_f32 v[72:73], v[54:55], v[62:63], v[52:53] op_sel:[0,0,1] op_sel_hi:[1,1,0] neg_lo:[0,0,1] neg_hi:[0,0,1]
	v_pk_fma_f32 v[52:53], v[54:55], v[62:63], v[52:53] op_sel:[0,0,1] op_sel_hi:[1,1,0]
	s_nop 0
	v_mov_b32_e32 v73, v53
	s_waitcnt lgkmcnt(12)
	v_pk_add_f32 v[62:63], v[72:73], v[100:101]
	ds_read_b32 v114, v154 offset:4224
	ds_read_b32 v115, v154 offset:4480
	s_nop 0
	v_cvt_pk_bf16_f32 v139, v62, v63
	v_pk_mul_f32 v[52:53], v[56:57], v[62:63]
	s_nop 0
	v_pk_fma_f32 v[72:73], v[54:55], v[62:63], v[52:53] op_sel:[0,0,1] op_sel_hi:[1,1,0] neg_lo:[0,0,1] neg_hi:[0,0,1]
	v_pk_fma_f32 v[52:53], v[54:55], v[62:63], v[52:53] op_sel:[0,0,1] op_sel_hi:[1,1,0]
	s_nop 0
	v_mov_b32_e32 v73, v53
	s_waitcnt lgkmcnt(12)
	v_pk_add_f32 v[62:63], v[72:73], v[102:103]
	ds_read_b32 v116, v154 offset:4752
	ds_read_b32 v117, v154 offset:5008
	s_nop 0
	v_cvt_pk_bf16_f32 v140, v62, v63
	v_pk_mul_f32 v[52:53], v[56:57], v[62:63]
	s_nop 0
	v_pk_fma_f32 v[72:73], v[54:55], v[62:63], v[52:53] op_sel:[0,0,1] op_sel_hi:[1,1,0] neg_lo:[0,0,1] neg_hi:[0,0,1]
	v_pk_fma_f32 v[52:53], v[54:55], v[62:63], v[52:53] op_sel:[0,0,1] op_sel_hi:[1,1,0]
	s_nop 0
	v_mov_b32_e32 v73, v53
	s_waitcnt lgkmcnt(12)
	v_pk_add_f32 v[62:63], v[72:73], v[104:105]
	ds_read_b32 v118, v154 offset:5280
	ds_read_b32 v119, v154 offset:5536
	s_nop 0
	v_cvt_pk_bf16_f32 v141, v62, v63
	v_pk_mul_f32 v[52:53], v[56:57], v[62:63]
	s_nop 0
	v_pk_fma_f32 v[72:73], v[54:55], v[62:63], v[52:53] op_sel:[0,0,1] op_sel_hi:[1,1,0] neg_lo:[0,0,1] neg_hi:[0,0,1]
	v_pk_fma_f32 v[52:53], v[54:55], v[62:63], v[52:53] op_sel:[0,0,1] op_sel_hi:[1,1,0]
	s_nop 0
	v_mov_b32_e32 v73, v53
	s_waitcnt lgkmcnt(12)
	v_pk_add_f32 v[62:63], v[72:73], v[106:107]
	ds_read_b32 v120, v154 offset:5808
	ds_read_b32 v121, v154 offset:6064
	s_nop 0
	v_cvt_pk_bf16_f32 v142, v62, v63
	v_pk_mul_f32 v[52:53], v[56:57], v[62:63]
	s_nop 0
	v_pk_fma_f32 v[72:73], v[54:55], v[62:63], v[52:53] op_sel:[0,0,1] op_sel_hi:[1,1,0] neg_lo:[0,0,1] neg_hi:[0,0,1]
	v_pk_fma_f32 v[52:53], v[54:55], v[62:63], v[52:53] op_sel:[0,0,1] op_sel_hi:[1,1,0]
	s_nop 0
	v_mov_b32_e32 v73, v53
	s_waitcnt lgkmcnt(12)
	v_pk_add_f32 v[62:63], v[72:73], v[108:109]
	ds_read_b32 v122, v154 offset:6336
	ds_read_b32 v123, v154 offset:6592
	s_nop 0
	v_cvt_pk_bf16_f32 v143, v62, v63
	v_pk_mul_f32 v[52:53], v[56:57], v[62:63]
	s_nop 0
	v_pk_fma_f32 v[72:73], v[54:55], v[62:63], v[52:53] op_sel:[0,0,1] op_sel_hi:[1,1,0] neg_lo:[0,0,1] neg_hi:[0,0,1]
	v_pk_fma_f32 v[52:53], v[54:55], v[62:63], v[52:53] op_sel:[0,0,1] op_sel_hi:[1,1,0]
	s_nop 0
	v_mov_b32_e32 v73, v53
	s_waitcnt lgkmcnt(12)
	v_pk_add_f32 v[62:63], v[72:73], v[110:111]
	ds_read_b32 v124, v154 offset:6864
	ds_read_b32 v125, v154 offset:7120
	s_nop 0
	v_cvt_pk_bf16_f32 v144, v62, v63
	v_pk_mul_f32 v[52:53], v[56:57], v[62:63]
	s_nop 0
	v_pk_fma_f32 v[72:73], v[54:55], v[62:63], v[52:53] op_sel:[0,0,1] op_sel_hi:[1,1,0] neg_lo:[0,0,1] neg_hi:[0,0,1]
	v_pk_fma_f32 v[52:53], v[54:55], v[62:63], v[52:53] op_sel:[0,0,1] op_sel_hi:[1,1,0]
	s_nop 0
	v_mov_b32_e32 v73, v53
	s_waitcnt lgkmcnt(12)
	v_pk_add_f32 v[62:63], v[72:73], v[112:113]
	ds_read_b32 v126, v154 offset:7392
	ds_read_b32 v127, v154 offset:7648
	s_nop 0
	v_cvt_pk_bf16_f32 v145, v62, v63
	v_pk_mul_f32 v[52:53], v[56:57], v[62:63]
	s_nop 0
	v_pk_fma_f32 v[72:73], v[54:55], v[62:63], v[52:53] op_sel:[0,0,1] op_sel_hi:[1,1,0] neg_lo:[0,0,1] neg_hi:[0,0,1]
	v_pk_fma_f32 v[52:53], v[54:55], v[62:63], v[52:53] op_sel:[0,0,1] op_sel_hi:[1,1,0]
	s_nop 0
	v_mov_b32_e32 v73, v53
	s_waitcnt lgkmcnt(12)
	v_pk_add_f32 v[62:63], v[72:73], v[114:115]
	ds_read_b32 v128, v154 offset:7920
	ds_read_b32 v129, v154 offset:8176
	s_nop 0
	v_cvt_pk_bf16_f32 v146, v62, v63
	v_pk_mul_f32 v[52:53], v[56:57], v[62:63]
	s_nop 0
	v_pk_fma_f32 v[72:73], v[54:55], v[62:63], v[52:53] op_sel:[0,0,1] op_sel_hi:[1,1,0] neg_lo:[0,0,1] neg_hi:[0,0,1]
	v_pk_fma_f32 v[52:53], v[54:55], v[62:63], v[52:53] op_sel:[0,0,1] op_sel_hi:[1,1,0]
	s_nop 0
	v_mov_b32_e32 v73, v53
	s_waitcnt lgkmcnt(12)
	v_pk_add_f32 v[62:63], v[72:73], v[116:117]
	s_nop 0
	v_cvt_pk_bf16_f32 v147, v62, v63
	v_pk_mul_f32 v[52:53], v[56:57], v[62:63]
	s_nop 0
	v_pk_fma_f32 v[72:73], v[54:55], v[62:63], v[52:53] op_sel:[0,0,1] op_sel_hi:[1,1,0] neg_lo:[0,0,1] neg_hi:[0,0,1]
	v_pk_fma_f32 v[52:53], v[54:55], v[62:63], v[52:53] op_sel:[0,0,1] op_sel_hi:[1,1,0]
	s_nop 0
	v_mov_b32_e32 v73, v53
	s_waitcnt lgkmcnt(10)
	v_pk_add_f32 v[62:63], v[72:73], v[118:119]
	s_nop 0
	v_cvt_pk_bf16_f32 v148, v62, v63
	v_pk_mul_f32 v[52:53], v[56:57], v[62:63]
	s_nop 0
	v_pk_fma_f32 v[72:73], v[54:55], v[62:63], v[52:53] op_sel:[0,0,1] op_sel_hi:[1,1,0] neg_lo:[0,0,1] neg_hi:[0,0,1]
	v_pk_fma_f32 v[52:53], v[54:55], v[62:63], v[52:53] op_sel:[0,0,1] op_sel_hi:[1,1,0]
	s_nop 0
	v_mov_b32_e32 v73, v53
	s_waitcnt lgkmcnt(8)
	v_pk_add_f32 v[62:63], v[72:73], v[120:121]
	s_nop 0
	v_cvt_pk_bf16_f32 v149, v62, v63
	v_pk_mul_f32 v[52:53], v[56:57], v[62:63]
	s_nop 0
	v_pk_fma_f32 v[72:73], v[54:55], v[62:63], v[52:53] op_sel:[0,0,1] op_sel_hi:[1,1,0] neg_lo:[0,0,1] neg_hi:[0,0,1]
	v_pk_fma_f32 v[52:53], v[54:55], v[62:63], v[52:53] op_sel:[0,0,1] op_sel_hi:[1,1,0]
	s_nop 0
	v_mov_b32_e32 v73, v53
	s_waitcnt lgkmcnt(6)
	v_pk_add_f32 v[62:63], v[72:73], v[122:123]
	s_nop 0
	v_cvt_pk_bf16_f32 v150, v62, v63
	v_pk_mul_f32 v[52:53], v[56:57], v[62:63]
	s_nop 0
	v_pk_fma_f32 v[72:73], v[54:55], v[62:63], v[52:53] op_sel:[0,0,1] op_sel_hi:[1,1,0] neg_lo:[0,0,1] neg_hi:[0,0,1]
	v_pk_fma_f32 v[52:53], v[54:55], v[62:63], v[52:53] op_sel:[0,0,1] op_sel_hi:[1,1,0]
	s_nop 0
	v_mov_b32_e32 v73, v53
	s_waitcnt lgkmcnt(4)
	v_pk_add_f32 v[62:63], v[72:73], v[124:125]
	s_nop 0
	v_cvt_pk_bf16_f32 v151, v62, v63
	v_pk_mul_f32 v[52:53], v[56:57], v[62:63]
	s_nop 0
	v_pk_fma_f32 v[72:73], v[54:55], v[62:63], v[52:53] op_sel:[0,0,1] op_sel_hi:[1,1,0] neg_lo:[0,0,1] neg_hi:[0,0,1]
	v_pk_fma_f32 v[52:53], v[54:55], v[62:63], v[52:53] op_sel:[0,0,1] op_sel_hi:[1,1,0]
	s_nop 0
	v_mov_b32_e32 v73, v53
	s_waitcnt lgkmcnt(2)
	v_pk_add_f32 v[62:63], v[72:73], v[126:127]
	s_nop 0
	v_cvt_pk_bf16_f32 v152, v62, v63
	v_pk_mul_f32 v[52:53], v[56:57], v[62:63]
	s_nop 0
	v_pk_fma_f32 v[72:73], v[54:55], v[62:63], v[52:53] op_sel:[0,0,1] op_sel_hi:[1,1,0] neg_lo:[0,0,1] neg_hi:[0,0,1]
	v_pk_fma_f32 v[52:53], v[54:55], v[62:63], v[52:53] op_sel:[0,0,1] op_sel_hi:[1,1,0]
	s_nop 0
	v_mov_b32_e32 v73, v53
	s_waitcnt lgkmcnt(0)
	v_pk_add_f32 v[62:63], v[72:73], v[128:129]
	s_nop 0
	v_cvt_pk_bf16_f32 v153, v62, v63
	ds_write_b32 v155, v138 offset:0
	ds_write_b32 v155, v139 offset:272
	ds_write_b32 v155, v140 offset:544
	ds_write_b32 v155, v141 offset:816
	ds_write_b32 v155, v142 offset:1088
	ds_write_b32 v155, v143 offset:1360
	ds_write_b32 v155, v144 offset:1632
	ds_write_b32 v155, v145 offset:1904
	ds_write_b32 v155, v146 offset:2176
	ds_write_b32 v155, v147 offset:2448
	ds_write_b32 v155, v148 offset:2720
	ds_write_b32 v155, v149 offset:2992
	ds_write_b32 v155, v150 offset:3264
	ds_write_b32 v155, v151 offset:3536
	ds_write_b32 v155, v152 offset:3808
	ds_write_b32 v155, v153 offset:4080
	s_waitcnt lgkmcnt(0)
	ds_read_b128 v[50:53], v69 offset:49152
	ds_read_b128 v[72:75], v69 offset:49216
	s_waitcnt lgkmcnt(1)
	v_mfma_f32_16x16x32_bf16 v[50:53], v[50:53], v[34:37], 0
	s_waitcnt lgkmcnt(0)
	v_mfma_f32_16x16x32_bf16 v[50:53], v[72:75], v[38:41], v[50:53]
	ds_read_b128 v[72:75], v69 offset:49280
	s_waitcnt lgkmcnt(0)
	v_mfma_f32_16x16x32_bf16 v[50:53], v[72:75], v[42:45], v[50:53]
	ds_read_b128 v[72:75], v69 offset:49344
	s_waitcnt lgkmcnt(0)
	v_mfma_f32_16x16x32_bf16 v[50:53], v[72:75], v[46:49], v[50:53]
	v_lshl_or_b32 v74, s35, 4, v87
	v_lshl_add_u32 v72, v74, 6, v88
	ds_read_b32 v72, v72 offset:16384
	s_add_i32 s35, s35, 1
	s_cmp_eq_u32 s35, 4
	s_waitcnt lgkmcnt(0)
	s_nop 1
	v_fma_f32 v50, v66, v72, v50
	v_mul_f32_e32 v72, 0x3d372713, v50
	v_mul_f32_e32 v72, v50, v72
	v_fma_f32 v72, v50, v72, v50
	v_mul_f32_e32 v72, 0x3f4c422a, v72
	v_add_f32_e32 v72, v72, v72
	v_mul_f32_e32 v72, 0x3fb8aa3b, v72
	v_exp_f32_e32 v72, v72
	v_mul_f32_e32 v50, 0.5, v50
	v_add_f32_e32 v72, 1.0, v72
	v_rcp_f32_e32 v72, v72
	s_nop 0
	v_fma_f32 v72, v72, -2.0, 1.0
	v_add_f32_e32 v72, 1.0, v72
	v_mul_f32_e32 v50, v50, v72
	v_or_b32_e32 v72, s25, v74
	v_ashrrev_i32_e32 v73, 31, v72
	v_lshlrev_b64 v[72:73], 10, v[72:73]
	v_cvt_pk_bf16_f32 v50, v50, 0
	v_lshl_add_u64 v[72:73], v[60:61], 0, v[72:73]
	global_store_short v[72:73], v50, off
	v_or_b32_e32 v50, 1, v74
	v_lshl_add_u32 v72, v50, 6, v88
	ds_read_b32 v72, v72 offset:16384
	v_or_b32_e32 v50, s25, v50
	s_waitcnt lgkmcnt(0)
	v_fma_f32 v51, v66, v72, v51
	v_mul_f32_e32 v72, 0x3d372713, v51
	v_mul_f32_e32 v72, v51, v72
	v_fma_f32 v72, v51, v72, v51
	v_mul_f32_e32 v72, 0x3f4c422a, v72
	v_add_f32_e32 v72, v72, v72
	v_mul_f32_e32 v72, 0x3fb8aa3b, v72
	v_exp_f32_e32 v72, v72
	v_mul_f32_e32 v51, 0.5, v51
	v_add_f32_e32 v72, 1.0, v72
	v_rcp_f32_e32 v72, v72
	s_nop 0
	v_fma_f32 v72, v72, -2.0, 1.0
	v_add_f32_e32 v72, 1.0, v72
	v_mul_f32_e32 v51, v51, v72
	v_cvt_pk_bf16_f32 v72, v51, 0
	v_ashrrev_i32_e32 v51, 31, v50
	v_lshlrev_b64 v[50:51], 10, v[50:51]
	v_lshl_add_u64 v[50:51], v[60:61], 0, v[50:51]
	global_store_short v[50:51], v72, off
	v_or_b32_e32 v50, 2, v74
	v_lshl_add_u32 v51, v50, 6, v88
	ds_read_b32 v51, v51 offset:16384
	v_or_b32_e32 v50, s25, v50
	s_waitcnt lgkmcnt(0)
	v_fma_f32 v51, v66, v51, v52
	v_mul_f32_e32 v52, 0x3d372713, v51
	v_mul_f32_e32 v52, v51, v52
	v_fma_f32 v52, v51, v52, v51
	v_mul_f32_e32 v52, 0x3f4c422a, v52
	v_add_f32_e32 v52, v52, v52
	v_mul_f32_e32 v52, 0x3fb8aa3b, v52
	v_exp_f32_e32 v52, v52
	v_mul_f32_e32 v51, 0.5, v51
	v_add_f32_e32 v52, 1.0, v52
	v_rcp_f32_e32 v52, v52
	s_nop 0
	v_fma_f32 v52, v52, -2.0, 1.0
	v_add_f32_e32 v52, 1.0, v52
	v_mul_f32_e32 v51, v51, v52
	v_cvt_pk_bf16_f32 v52, v51, 0
	v_ashrrev_i32_e32 v51, 31, v50
	v_lshlrev_b64 v[50:51], 10, v[50:51]
	v_lshl_add_u64 v[50:51], v[60:61], 0, v[50:51]
	global_store_short v[50:51], v52, off
	v_or_b32_e32 v50, 3, v74
	v_lshl_add_u32 v51, v50, 6, v88
	ds_read_b32 v51, v51 offset:16384
	v_or_b32_e32 v50, s25, v50
	s_waitcnt lgkmcnt(0)
	v_fmac_f32_e32 v53, v66, v51
	v_mul_f32_e32 v51, 0x3d372713, v53
	v_mul_f32_e32 v51, v53, v51
	v_fma_f32 v51, v53, v51, v53
	v_mul_f32_e32 v51, 0x3f4c422a, v51
	v_add_f32_e32 v51, v51, v51
	v_mul_f32_e32 v51, 0x3fb8aa3b, v51
	v_exp_f32_e32 v51, v51
	v_mul_f32_e32 v52, 0.5, v53
	v_add_f32_e32 v51, 1.0, v51
	v_rcp_f32_e32 v51, v51
	s_nop 0
	v_fma_f32 v51, v51, -2.0, 1.0
	v_add_f32_e32 v51, 1.0, v51
	v_mul_f32_e32 v51, v52, v51
	v_cvt_pk_bf16_f32 v52, v51, 0
	v_ashrrev_i32_e32 v51, 31, v50
	v_lshlrev_b64 v[50:51], 10, v[50:51]
	v_lshl_add_u64 v[50:51], v[60:61], 0, v[50:51]
	global_store_short v[50:51], v52, off
	s_waitcnt lgkmcnt(0)
	s_cbranch_scc0 .LBB0_982
	s_add_i32 s21, s21, 1
	s_cmp_eq_u32 s21, 4
	s_cbranch_scc0 .LBB0_981
	s_add_i32 s34, s34, s59
	s_cmpk_lt_i32 s34, 0x200
	s_barrier
	s_cbranch_scc1 .LBB0_944
	v_readlane_b32 s0, v253, 38
	v_readlane_b32 s8, v253, 46
	v_readlane_b32 s14, v253, 52
	v_readlane_b32 s9, v253, 47
	v_readlane_b32 s15, v253, 53
	s_add_u32 s8, s14, 0x34e00000
	v_readlane_b32 s10, v253, 48
	s_addc_u32 s9, s15, 0
	v_readlane_b32 s11, v253, 49
	v_readlane_b32 s12, v253, 50
	v_readlane_b32 s13, v253, 51
	s_add_u32 s10, s14, 0x9a00800
	s_addc_u32 s11, s15, 0
	v_readlane_b32 s12, v253, 6
	s_mov_b32 s13, s58
	v_readlane_b32 s1, v253, 39
	v_readlane_b32 s2, v253, 40
	v_readlane_b32 s3, v253, 41
	v_readlane_b32 s4, v253, 42
	v_readlane_b32 s5, v253, 43
	v_readlane_b32 s6, v253, 44
	v_readlane_b32 s7, v253, 45
